# wave 0 takes the phase-header results from wave 1 through LDS instead of re-running the header after the grid barrier
# baseline (speedup 1.0000x reference)
.LBB0_5:
	s_or_b64 exec, exec, s[6:7]
	s_load_dwordx2 s[96:97], s[94:95], 0xa8
	s_waitcnt lgkmcnt(0)
	s_cmp_ge_i32 s96, s97
	s_cbranch_scc1 .LBB0_551
	s_cmp_lt_i32 s2, 64
	s_cselect_b64 s[6:7], -1, 0
	v_writelane_b32 v252, s6, 4
	s_ashr_i32 s3, s2, 31
	s_load_dwordx2 s[56:57], s[94:95], 0xb0
	v_writelane_b32 v252, s7, 5
	s_lshr_b32 s6, s3, 29
	s_add_i32 s6, s2, s6
	s_ashr_i32 s90, s6, 3
	s_and_b32 s6, s6, -8
	s_sub_i32 s93, s2, s6
	s_cmp_lt_i32 s93, 0
	s_cselect_b64 s[98:99], -1, 0
	s_lshl_b32 s6, s2, 5
	s_ashr_i32 s23, s16, 31
	v_writelane_b32 v252, s6, 6
	s_lshl_b32 s52, s16, 5
	s_lshl_b32 s8, s2, 3
	s_lshl_b32 s54, s16, 3
	s_lshl_b32 s6, s2, 9
	s_lshl_b32 s58, s16, 9
	s_cmp_eq_u32 s2, 0
	v_writelane_b32 v252, s6, 7
	s_cselect_b64 s[6:7], -1, 0
	v_writelane_b32 v252, s6, 8
	v_lshrrev_b32_e32 v1, 20, v0
	v_lshrrev_b32_e32 v0, 10, v0
	v_writelane_b32 v252, s7, 9
	s_waitcnt lgkmcnt(0)
	s_max_i32 s6, s56, 1
	s_add_i32 s34, s6, -1
	s_add_u32 s12, s0, 0x10200
	s_addc_u32 s13, s1, 0
	s_add_u32 s14, s0, 0x10400
	s_addc_u32 s15, s1, 0
	s_add_u32 s36, s0, 0x10500
	s_addc_u32 s37, s1, 0
	s_add_u32 s60, s0, 0x10600
	v_writelane_b32 v252, s12, 10
	s_addc_u32 s61, s1, 0
	v_or_b32_e32 v0, v0, v1
	v_writelane_b32 v252, s13, 11
	s_add_u32 s12, s0, 0x10700
	s_addc_u32 s13, s1, 0
	v_writelane_b32 v252, s12, 12
	s_mov_b32 s35, 0
	s_mov_b64 s[68:69], s[34:35]
	v_writelane_b32 v252, s13, 13
	s_add_u32 s12, s0, 0x10800
	s_addc_u32 s13, s1, 0
	v_writelane_b32 v252, s12, 14
	v_mbcnt_lo_u32_b32 v1, -1, 0
	s_mov_b32 s26, 0xc1d00000
	v_writelane_b32 v252, s13, 15
	s_add_u32 s12, s0, 0x10900
	s_addc_u32 s13, s1, 0
	v_writelane_b32 v252, s12, 16
	v_mbcnt_hi_u32_b32 v221, -1, v1
	v_mov_b32_e32 v193, 0
	v_writelane_b32 v252, s13, 17
	s_add_u32 s12, s0, 0x10a00
	s_addc_u32 s13, s1, 0
	v_writelane_b32 v252, s12, 18
	s_mov_b32 s27, 0xc1d80000
	v_mov_b32_e32 v217, 0x358637bd
	v_writelane_b32 v252, s13, 19
	s_add_u32 s12, s0, 0x10b00
	s_addc_u32 s13, s1, 0
	v_writelane_b32 v252, s12, 20
	v_mov_b32_e32 v218, 0x260
	v_mov_b32_e32 v219, 0x3727c5ac
	v_writelane_b32 v252, s13, 21
	s_add_u32 s12, s0, 0x10c00
	s_addc_u32 s13, s1, 0
	v_writelane_b32 v252, s12, 22
	v_mov_b32_e32 v220, 1
	v_and_b32_e32 v222, 64, v221
	v_writelane_b32 v252, s13, 23
	s_add_u32 s12, s0, 0x10d00
	s_addc_u32 s13, s1, 0
	v_writelane_b32 v252, s12, 24
	v_add_u32_e32 v223, -1, v221
	v_add_u32_e32 v224, -2, v221
	v_writelane_b32 v252, s13, 25
	s_add_u32 s12, s0, 0x10e00
	s_addc_u32 s13, s1, 0
	v_writelane_b32 v252, s12, 26
	v_add_u32_e32 v225, -4, v221
	v_add_u32_e32 v226, -8, v221
	v_writelane_b32 v252, s13, 27
	s_add_u32 s12, s0, 0x10f00
	s_addc_u32 s13, s1, 0
	v_writelane_b32 v252, s12, 28
	v_add_u32_e32 v227, -16, v221
	v_subrev_u32_e32 v228, 32, v221
	v_writelane_b32 v252, s13, 29
	s_add_u32 s12, s0, 0x11000
	s_addc_u32 s13, s1, 0
	v_writelane_b32 v252, s12, 30
	v_mov_b32_e32 v229, 0xf149f2ca
	v_mov_b32_e32 v230, 0x30000
	v_writelane_b32 v252, s13, 31
	s_add_u32 s12, s0, 0x11100
	s_addc_u32 s13, s1, 0
	v_writelane_b32 v252, s12, 32
	v_mov_b32_e32 v231, 0x7f800000
	v_mov_b32_e32 v210, 0x3f317218
	v_writelane_b32 v252, s13, 33
	s_add_u32 s12, s0, 0x11200
	s_addc_u32 s13, s1, 0
	v_writelane_b32 v252, s12, 34
	v_mov_b32_e32 v234, 0x3c23d70a
	v_mov_b32_e32 v235, 0x3bb8449c
	v_writelane_b32 v252, s13, 35
	s_add_u32 s12, s0, 0x11300
	s_addc_u32 s13, s1, 0
	v_writelane_b32 v252, s12, 36
	s_cmp_eq_u32 s10, 15
	v_mov_b32_e32 v236, 0x3b4f3e37
	v_writelane_b32 v252, s13, 37
	s_cselect_b64 s[12:13], -1, 0
	v_writelane_b32 v252, s12, 38
	s_cmp_eq_u32 s10, 14
	v_mov_b32_e32 v237, 0x3ae91528
	v_writelane_b32 v252, s13, 39
	s_cselect_b64 s[12:13], -1, 0
	v_writelane_b32 v252, s12, 40
	s_cmp_eq_u32 s10, 13
	v_mov_b32_e32 v238, 0x3a83126f
	v_writelane_b32 v252, s13, 41
	s_cselect_b64 s[12:13], -1, 0
	v_writelane_b32 v252, s12, 42
	s_cmp_eq_u32 s10, 12
	v_mov_b32_e32 v239, 0x3a136a16
	v_writelane_b32 v252, s13, 43
	s_cselect_b64 s[12:13], -1, 0
	v_writelane_b32 v252, s12, 44
	s_cmp_eq_u32 s10, 11
	v_mov_b32_e32 v240, 0x39a5cb5f
	v_writelane_b32 v252, s13, 45
	s_cselect_b64 s[12:13], -1, 0
	v_writelane_b32 v252, s12, 46
	s_cmp_eq_u32 s10, 10
	v_mov_b32_e32 v241, 0x393a7753
	v_writelane_b32 v252, s13, 47
	s_cselect_b64 s[12:13], -1, 0
	v_writelane_b32 v252, s12, 48
	s_cmp_eq_u32 s10, 9
	s_mov_b32 s91, 0x7fffffe0
	v_writelane_b32 v252, s13, 49
	s_cselect_b64 s[12:13], -1, 0
	v_writelane_b32 v252, s12, 50
	s_cmp_eq_u32 s10, 8
	s_movk_i32 s92, 0x1600
	v_writelane_b32 v252, s13, 51
	s_cselect_b64 s[12:13], -1, 0
	v_writelane_b32 v252, s12, 52
	s_cmp_eq_u32 s10, 7
	s_mov_b32 s33, 0x41000000
	v_writelane_b32 v252, s13, 53
	s_cselect_b64 s[12:13], -1, 0
	v_writelane_b32 v252, s12, 54
	s_cmp_eq_u32 s10, 6
	s_mov_b32 s34, 0x3fb8aa3b
	v_writelane_b32 v252, s13, 55
	s_cselect_b64 s[12:13], -1, 0
	v_writelane_b32 v252, s12, 56
	s_cmp_eq_u32 s10, 5
	s_mov_b64 s[24:25], 0x80
	v_writelane_b32 v252, s13, 57
	s_cselect_b64 s[12:13], -1, 0
	v_writelane_b32 v252, s12, 58
	s_cmp_eq_u32 s10, 4
	s_mov_b32 s22, 0x3fb504f3
	v_writelane_b32 v252, s13, 59
	s_cselect_b64 s[12:13], -1, 0
	v_writelane_b32 v252, s12, 60
	s_cmp_eq_u32 s10, 3
	s_nop 0
	v_writelane_b32 v252, s13, 61
	s_cselect_b64 s[12:13], -1, 0
	v_writelane_b32 v252, s12, 62
	s_cmp_eq_u32 s10, 2
	s_nop 0
	v_writelane_b32 v252, s13, 63
	s_cselect_b64 s[12:13], -1, 0
	v_writelane_b32 v253, s12, 0
	s_cmp_eq_u32 s10, 1
	s_nop 0
	v_writelane_b32 v253, s13, 1
	s_cselect_b64 s[12:13], -1, 0
	v_writelane_b32 v253, s12, 2
	s_cmp_eq_u32 s10, 0
	s_nop 0
	v_writelane_b32 v253, s13, 3
	s_cselect_b64 s[12:13], -1, 0
	s_lshl_b32 s7, s10, 8
	s_add_u32 s4, s4, s7
	s_addc_u32 s5, s5, 0
	v_writelane_b32 v253, s12, 4
	s_add_u32 s10, s4, 0x1400
	s_addc_u32 s11, s5, 0
	v_writelane_b32 v253, s13, 5
	v_writelane_b32 v253, s10, 6
	s_add_u32 s4, s4, 0x2400
	s_addc_u32 s5, s5, 0
	v_writelane_b32 v253, s11, 7
	v_writelane_b32 v253, s4, 8
	s_nop 1
	v_writelane_b32 v253, s5, 9
	s_add_u32 s4, s0, 0x13400
	s_addc_u32 s5, s1, 0
	v_writelane_b32 v253, s4, 10
	s_add_u32 s0, s0, 0x13500
	s_addc_u32 s1, s1, 0
	v_writelane_b32 v253, s5, 11
	v_writelane_b32 v253, s0, 12
	s_cmp_lt_i32 s97, 19
	s_nop 0
	v_writelane_b32 v253, s1, 13
	s_load_dword s1, s[94:95], 0x6e0
	s_mul_i32 s0, s17, s16
	s_waitcnt lgkmcnt(0)
	s_mul_i32 s0, s0, s1
	v_writelane_b32 v253, s0, 14
	s_movk_i32 s0, 0x3ff
	v_and_or_b32 v0, v0, s0, v216
	s_cselect_b64 s[0:1], -1, 0
	v_writelane_b32 v253, s0, 15
	s_add_u32 s62, s94, 0x120
	s_addc_u32 s63, s95, 0
	v_writelane_b32 v253, s1, 16
	v_writelane_b32 v253, s8, 17
	s_add_i32 s0, s8, s54
	v_writelane_b32 v253, s0, 18
	s_add_i32 s0, 0, 0x15500
	v_writelane_b32 v253, s0, 19
	s_add_i32 s0, 0, 0x14500
	v_writelane_b32 v253, s0, 20
	s_add_i32 s0, 0, 0x14900
	v_writelane_b32 v253, s0, 21
	s_add_i32 s0, 0, 0x23fc0
	v_writelane_b32 v253, s0, 22
	s_add_i32 s0, 0, 0x23fc4
	v_writelane_b32 v253, s0, 23
	s_load_dwordx2 s[66:67], s[94:95], 0x0
	s_load_dwordx2 s[0:1], s[94:95], 0x30
	s_add_u32 s17, s6, -1
	s_load_dwordx4 s[4:7], s[94:95], 0x60
	s_ashr_i32 s55, s54, 31
	s_ashr_i32 s59, s58, 31
	s_waitcnt lgkmcnt(0)
	v_writelane_b32 v253, s0, 24
	s_lshl_b64 s[88:89], s[58:59], 2
	s_lshl_b32 s53, s16, 10
	v_writelane_b32 v253, s1, 25
	s_load_dwordx2 s[0:1], s[94:95], 0x50
	s_waitcnt lgkmcnt(0)
	v_writelane_b32 v253, s0, 26
	s_nop 1
	v_writelane_b32 v253, s1, 27
	v_cmp_eq_u32_e64 s[0:1], 0, v0
	s_nop 1
	v_writelane_b32 v253, s0, 28
	s_nop 1
	v_writelane_b32 v253, s1, 29
	s_lshl_b64 s[0:1], s[54:55], 3
	v_writelane_b32 v253, s0, 30
	s_nop 1
	v_writelane_b32 v253, s1, 31
	s_lshl_b64 s[0:1], s[54:55], 5
	v_writelane_b32 v253, s0, 32
	s_nop 1
	v_writelane_b32 v253, s1, 33
	s_lshl_b64 s[0:1], s[54:55], 11
	v_writelane_b32 v253, s0, 34
	s_nop 1
	v_writelane_b32 v253, s1, 35
	s_lshl_b64 s[0:1], s[54:55], 12
	v_writelane_b32 v253, s0, 36
	s_nop 1
	v_writelane_b32 v253, s1, 37
	v_writelane_b32 v253, s4, 38
	s_mov_b32 s0, 0xc2000000
	s_nop 0
	v_writelane_b32 v253, s5, 39
	v_writelane_b32 v253, s6, 40
	v_writelane_b32 v253, s7, 41
	s_load_dwordx4 s[84:87], s[94:95], 0x40
	s_load_dwordx8 s[4:11], s[94:95], 0x88
	s_waitcnt lgkmcnt(0)
	v_writelane_b32 v253, s4, 42
	s_nop 1
	v_writelane_b32 v253, s5, 43
	v_writelane_b32 v253, s6, 44
	v_writelane_b32 v253, s7, 45
	v_writelane_b32 v253, s8, 46
	v_writelane_b32 v253, s9, 47
	v_writelane_b32 v253, s10, 48
	v_writelane_b32 v253, s11, 49
	v_writelane_b32 v253, s88, 50
	s_nop 1
	v_writelane_b32 v253, s89, 51
	v_writelane_b32 v253, s84, 52
	s_nop 1
	v_writelane_b32 v253, s85, 53
	v_writelane_b32 v253, s86, 54
	v_writelane_b32 v253, s87, 55
	v_writelane_b32 v253, s94, 56
	s_nop 1
	v_writelane_b32 v253, s95, 57
	v_writelane_b32 v253, s98, 58
	s_nop 1
	v_writelane_b32 v253, s99, 59
	v_writelane_b32 v253, s52, 60
	v_writelane_b32 v253, s54, 61
	s_nop 1
	v_writelane_b32 v253, s55, 62
	v_writelane_b32 v253, s56, 63
	s_nop 1
	v_writelane_b32 v254, s57, 0
	v_writelane_b32 v254, s58, 1
	s_nop 1
	v_writelane_b32 v254, s59, 2
	v_writelane_b32 v254, s14, 3
	s_nop 1
	v_writelane_b32 v254, s15, 4
	v_writelane_b32 v254, s36, 5
	s_nop 1
	v_writelane_b32 v254, s37, 6
	v_writelane_b32 v254, s60, 7
	s_nop 1
	v_writelane_b32 v254, s61, 8
	v_writelane_b32 v254, s90, 9
	v_writelane_b32 v254, s62, 10
	s_nop 1
	v_writelane_b32 v254, s63, 11
	v_writelane_b32 v254, s53, 12
	v_writelane_b32 v254, s66, 13
	s_nop 1
	v_writelane_b32 v254, s67, 14
	v_writelane_b32 v254, s68, 15
	s_nop 1
	v_writelane_b32 v254, s69, 16
	s_mov_b32 s32, 0
	s_branch .LBB0_11

.LBB0_11:
	s_cmp_eq_u32 s96, 11
	s_mov_b32 s1, 12
	s_cbranch_scc1 .LBB0_10
	s_cmp_eq_u32 s32, 0
	s_cbranch_scc1 .Lhdr_run
	v_readfirstlane_b32 s4, v216
	s_nop 3
	s_cmp_ge_u32 s4, 64
	s_cbranch_scc1 .Lhdr_run
	s_barrier
	s_mov_b32 s4, 0x23400
	v_lshl_add_u32 v0, v221, 2, s4
	ds_read_b32 v1, v0
	ds_read_b32 v2, v0 offset:256
	ds_read_b32 v254, v0 offset:512
	ds_read_b32 v255, v0 offset:768
	s_waitcnt lgkmcnt(0)
	v_readlane_b32 s0, v1, 0
	v_readlane_b32 s1, v1, 1
	v_readlane_b32 s2, v1, 2
	v_readlane_b32 s3, v1, 3
	v_readlane_b32 s4, v1, 4
	v_readlane_b32 s5, v1, 5
	v_readlane_b32 s6, v1, 6
	v_readlane_b32 s7, v1, 7
	v_readlane_b32 s8, v1, 8
	v_readlane_b32 s9, v1, 9
	v_readlane_b32 s10, v1, 10
	v_readlane_b32 s11, v1, 11
	v_readlane_b32 s12, v1, 12
	v_readlane_b32 s13, v1, 13
	v_readlane_b32 s14, v1, 14
	v_readlane_b32 s15, v1, 15
	v_readlane_b32 s16, v1, 16
	v_readlane_b32 s17, v1, 17
	v_readlane_b32 s18, v1, 18
	v_readlane_b32 s19, v1, 19
	v_readlane_b32 s20, v1, 20
	v_readlane_b32 s21, v1, 21
	v_readlane_b32 s22, v1, 22
	v_readlane_b32 s23, v1, 23
	v_readlane_b32 s24, v1, 24
	v_readlane_b32 s25, v1, 25
	v_readlane_b32 s26, v1, 26
	v_readlane_b32 s27, v1, 27
	v_readlane_b32 s28, v1, 28
	v_readlane_b32 s29, v1, 29
	v_readlane_b32 s30, v1, 30
	v_readlane_b32 s31, v1, 31
	v_readlane_b32 s33, v1, 33
	v_readlane_b32 s34, v1, 34
	v_readlane_b32 s35, v1, 35
	v_readlane_b32 s36, v1, 36
	v_readlane_b32 s37, v1, 37
	v_readlane_b32 s38, v1, 38
	v_readlane_b32 s39, v1, 39
	v_readlane_b32 s40, v1, 40
	v_readlane_b32 s41, v1, 41
	v_readlane_b32 s42, v1, 42
	v_readlane_b32 s43, v1, 43
	v_readlane_b32 s44, v1, 44
	v_readlane_b32 s45, v1, 45
	v_readlane_b32 s46, v1, 46
	v_readlane_b32 s47, v1, 47
	v_readlane_b32 s48, v1, 48
	v_readlane_b32 s49, v1, 49
	v_readlane_b32 s50, v1, 50
	v_readlane_b32 s51, v1, 51
	v_readlane_b32 s52, v1, 52
	v_readlane_b32 s53, v1, 53
	v_readlane_b32 s54, v1, 54
	v_readlane_b32 s55, v1, 55
	v_readlane_b32 s56, v1, 56
	v_readlane_b32 s57, v1, 57
	v_readlane_b32 s58, v1, 58
	v_readlane_b32 s59, v1, 59
	v_readlane_b32 s60, v1, 60
	v_readlane_b32 s61, v1, 61
	v_readlane_b32 s62, v1, 62
	v_readlane_b32 s63, v1, 63
	v_readlane_b32 s64, v2, 0
	v_readlane_b32 s65, v2, 1
	v_readlane_b32 s66, v2, 2
	v_readlane_b32 s67, v2, 3
	v_readlane_b32 s68, v2, 4
	v_readlane_b32 s69, v2, 5
	v_readlane_b32 s70, v2, 6
	v_readlane_b32 s71, v2, 7
	v_readlane_b32 s72, v2, 8
	v_readlane_b32 s73, v2, 9
	v_readlane_b32 s74, v2, 10
	v_readlane_b32 s75, v2, 11
	v_readlane_b32 s76, v2, 12
	v_readlane_b32 s77, v2, 13
	v_readlane_b32 s78, v2, 14
	v_readlane_b32 s79, v2, 15
	v_readlane_b32 s80, v2, 16
	v_readlane_b32 s81, v2, 17
	v_readlane_b32 s82, v2, 18
	v_readlane_b32 s83, v2, 19
	v_readlane_b32 s84, v2, 20
	v_readlane_b32 s85, v2, 21
	v_readlane_b32 s86, v2, 22
	v_readlane_b32 s87, v2, 23
	v_readlane_b32 s88, v2, 24
	v_readlane_b32 s89, v2, 25
	v_readlane_b32 s90, v2, 26
	v_readlane_b32 s91, v2, 27
	v_readlane_b32 s92, v2, 28
	v_readlane_b32 s93, v2, 29
	v_readlane_b32 s94, v2, 30
	v_readlane_b32 s95, v2, 31
	v_readlane_b32 s96, v2, 32
	v_readlane_b32 s97, v2, 33
	v_readlane_b32 s98, v2, 34
	v_readlane_b32 s99, v2, 35
	s_mov_b32 s32, 0
	s_branch .LBB0_59
.Lhdr_run:
	v_readlane_b32 s4, v253, 42
	v_readlane_b32 s5, v253, 43
	v_readlane_b32 s8, v253, 46
	v_readlane_b32 s9, v253, 47
	v_readlane_b32 s10, v253, 48
	v_readlane_b32 s11, v253, 49
	s_mov_b64 s[4:5], s[8:9]
	s_add_u32 s70, s10, 0x4000000
	v_writelane_b32 v254, s4, 17
	s_addc_u32 s71, s11, 0
	v_readlane_b32 s6, v253, 44
	v_writelane_b32 v254, s5, 18
	s_add_u32 s4, s10, 0x8000000
	s_addc_u32 s5, s11, 0
	v_writelane_b32 v254, s4, 19
	v_readlane_b32 s7, v253, 45
	s_mov_b64 s[40:41], -1
	v_writelane_b32 v254, s5, 20
	s_add_u32 s4, s10, 0x18000000
	s_addc_u32 s5, s11, 0
	v_writelane_b32 v254, s4, 21
	s_cmp_gt_i32 s96, 9
	s_mov_b64 s[8:9], 0
	v_writelane_b32 v254, s5, 22
	s_cselect_b64 s[4:5], -1, 0
	s_cmp_lt_i32 s96, 8
	s_mov_b64 s[28:29], 0
	s_mov_b64 s[30:31], 0
	s_cbranch_scc1 .LBB0_32
	s_mov_b64 s[12:13], 0
	v_writelane_b32 v254, s12, 23
	s_mov_b64 s[6:7], -1
	s_cmp_gt_i32 s96, 12
	v_writelane_b32 v254, s13, 24
	s_mov_b64 s[38:39], 0
	s_cbranch_scc0 .LBB0_20
	s_cmp_gt_i32 s96, 14
	s_cbranch_scc0 .LBB0_17
	s_mov_b64 s[40:41], 0
	s_mov_b64 s[30:31], -1
	s_cmp_gt_i32 s96, 15
	s_cbranch_scc0 .LBB0_17
	s_cmp_eq_u32 s96, 16
	s_mov_b64 s[30:31], 0
	s_cselect_b64 s[38:39], -1, 0

.LBB0_55:
	s_xor_b64 s[6:7], s[6:7], -1
	s_cmp_eq_u32 s96, -1
	v_writelane_b32 v254, s6, 60
	s_cselect_b32 s56, 2, 1
	s_cmp_eq_u32 s96, 10
	v_writelane_b32 v254, s7, 61
	s_cselect_b64 s[6:7], -1, 0
	s_add_u32 s59, s10, 0x3700000
	v_writelane_b32 v254, s6, 62
	s_addc_u32 s64, s11, 0
	s_mov_b32 s31, s35
	v_writelane_b32 v254, s7, 63
	s_add_u32 s6, s10, 0x3800000
	s_addc_u32 s7, s11, 0
	v_writelane_b32 v255, s6, 0
	v_alignbit_b32 v0, s96, s96, 1
	s_nop 0
	v_writelane_b32 v255, s7, 1
	v_readlane_b32 s6, v254, 39
	v_readlane_b32 s7, v254, 40
	s_cmp_eq_u64 s[6:7], 0
	s_cselect_b64 s[6:7], -1, 0
	v_writelane_b32 v255, s6, 2
	s_add_u32 s1, s10, 0xe000000
	v_readfirstlane_b32 s72, v0
	v_writelane_b32 v255, s7, 3
	v_writelane_b32 v255, s1, 4
	s_addc_u32 s1, s11, 0
	v_writelane_b32 v255, s1, 5
	s_add_u32 s1, s10, 0x10000000
	v_writelane_b32 v255, s1, 6
	s_addc_u32 s1, s11, 0
	v_writelane_b32 v255, s1, 7
	s_add_u32 s1, s10, 0x12000000
	v_writelane_b32 v255, s1, 8
	s_addc_u32 s1, s11, 0
	v_writelane_b32 v255, s1, 9
	s_add_u32 s1, s10, 0xa000000
	v_writelane_b32 v255, s1, 10
	s_addc_u32 s1, s11, 0
	v_writelane_b32 v255, s1, 11
	s_add_u32 s1, s10, 0xc000000
	v_writelane_b32 v255, s1, 12
	s_addc_u32 s1, s11, 0
	v_writelane_b32 v255, s1, 13
	s_add_u32 s1, s10, 0x8000540
	v_writelane_b32 v255, s1, 14
	s_addc_u32 s1, s11, 0
	v_writelane_b32 v255, s1, 15
	s_add_u32 s1, s10, 0x8000940
	v_writelane_b32 v255, s1, 16
	s_addc_u32 s1, s11, 0
	v_writelane_b32 v255, s1, 17
	s_add_u32 s1, s10, 0x8000a40
	v_writelane_b32 v255, s1, 18
	s_addc_u32 s1, s11, 0
	v_writelane_b32 v255, s1, 19
	s_add_u32 s1, s10, 0x11000000
	v_writelane_b32 v255, s1, 20
	s_addc_u32 s1, s11, 0
	s_add_u32 s6, s10, 0x3500000
	v_writelane_b32 v255, s1, 21
	s_addc_u32 s7, s11, 0
	v_writelane_b32 v255, s6, 22
	s_nop 1
	v_writelane_b32 v255, s7, 23
	s_add_u32 s6, s10, 0x100000
	s_addc_u32 s7, s11, 0
	v_writelane_b32 v255, s6, 24
	s_nop 1
	v_writelane_b32 v255, s7, 25
	s_add_u32 s6, s10, 0x140000
	s_addc_u32 s7, s11, 0
	v_writelane_b32 v255, s6, 26
	s_nop 1
	v_writelane_b32 v255, s7, 27
	s_add_u32 s6, s10, 0x3400000
	s_addc_u32 s7, s11, 0
	v_writelane_b32 v255, s6, 28
	s_nop 1
	v_writelane_b32 v255, s7, 29
	s_add_u32 s6, s10, 0x3480000
	s_addc_u32 s7, s11, 0
	v_writelane_b32 v255, s6, 30
	s_nop 1
	v_writelane_b32 v255, s7, 31
	s_add_u32 s6, s10, 0x3a00000
	v_writelane_b32 v255, s10, 32
	s_addc_u32 s7, s11, 0
	s_and_b32 s1, s96, -9
	v_writelane_b32 v255, s11, 33
	v_writelane_b32 v255, s6, 34
	s_and_b64 s[4:5], s[4:5], exec
	v_readlane_b32 s4, v254, 17
	v_writelane_b32 v255, s7, 35
	s_cselect_b32 s6, 0x400, 0
	s_cmp_eq_u32 s1, 6
	s_movk_i32 s1, 0x60
	s_cselect_b32 s1, s1, 0x88
	v_writelane_b32 v255, s1, 36
	s_movk_i32 s1, 0x68
	v_readlane_b32 s5, v254, 18
	s_cselect_b32 s1, s1, 0x90
	s_cmp_lg_u64 s[4:5], 0
	v_writelane_b32 v255, s1, 37
	s_cselect_b64 s[4:5], -1, 0
	v_readlane_b32 s1, v254, 57
	v_writelane_b32 v255, s4, 38
	s_lshl_b32 s30, s1, 8
	s_lshl_b32 s1, s83, 9
	v_writelane_b32 v255, s5, 39
	s_lshl_b64 s[4:5], s[30:31], 1
	v_writelane_b32 v255, s4, 40
	s_lshr_b32 s11, s83, 6
	s_lshl_b32 s10, s83, 8
	v_writelane_b32 v255, s5, 41
	v_writelane_b32 v255, s1, 42
	v_readlane_b32 s1, v254, 27
	s_lshr_b32 s7, s1, 4
	s_or_b32 s8, s7, 1
	s_add_i32 s1, s11, -2
	s_and_b64 s[4:5], s[98:99], exec
	s_cselect_b32 s4, s8, s7
	s_mul_i32 s4, s4, s93
	v_writelane_b32 v255, s7, 43
	s_add_i32 s4, s4, s90
	v_writelane_b32 v255, s8, 44
	s_ashr_i32 s5, s4, 31
	v_writelane_b32 v255, s5, 45
	v_writelane_b32 v255, s4, 46
	s_abs_i32 s4, s4
	v_writelane_b32 v255, s4, 47
	s_lshl_b32 s4, s6, 2
	v_writelane_b32 v255, s4, 48
	v_writelane_b32 v255, s70, 49
	s_nop 1
	v_writelane_b32 v255, s71, 50
	v_writelane_b32 v255, s83, 51
	v_writelane_b32 v255, s72, 52
	v_writelane_b32 v255, s96, 53
	s_nop 1
	v_writelane_b32 v255, s97, 54
	v_writelane_b32 v255, s56, 55
	v_writelane_b32 v255, s59, 56
	v_writelane_b32 v255, s64, 57
	s_cmp_eq_u32 s32, 0
	s_cbranch_scc1 .Lhdr_nopub
	v_readfirstlane_b32 vcc_lo, v216
	s_nop 3
	s_and_b32 vcc_lo, vcc_lo, 0xffffffc0
	s_cmp_eq_u32 vcc_lo, 64
	s_cbranch_scc0 .Lhdr_pubdone
	v_writelane_b32 v1, s0, 0
	v_writelane_b32 v1, s1, 1
	v_writelane_b32 v1, s2, 2
	v_writelane_b32 v1, s3, 3
	v_writelane_b32 v1, s4, 4
	v_writelane_b32 v1, s5, 5
	v_writelane_b32 v1, s6, 6
	v_writelane_b32 v1, s7, 7
	v_writelane_b32 v1, s8, 8
	v_writelane_b32 v1, s9, 9
	v_writelane_b32 v1, s10, 10
	v_writelane_b32 v1, s11, 11
	v_writelane_b32 v1, s12, 12
	v_writelane_b32 v1, s13, 13
	v_writelane_b32 v1, s14, 14
	v_writelane_b32 v1, s15, 15
	v_writelane_b32 v1, s16, 16
	v_writelane_b32 v1, s17, 17
	v_writelane_b32 v1, s18, 18
	v_writelane_b32 v1, s19, 19
	v_writelane_b32 v1, s20, 20
	v_writelane_b32 v1, s21, 21
	v_writelane_b32 v1, s22, 22
	v_writelane_b32 v1, s23, 23
	v_writelane_b32 v1, s24, 24
	v_writelane_b32 v1, s25, 25
	v_writelane_b32 v1, s26, 26
	v_writelane_b32 v1, s27, 27
	v_writelane_b32 v1, s28, 28
	v_writelane_b32 v1, s29, 29
	v_writelane_b32 v1, s30, 30
	v_writelane_b32 v1, s31, 31
	v_writelane_b32 v1, s33, 33
	v_writelane_b32 v1, s34, 34
	v_writelane_b32 v1, s35, 35
	v_writelane_b32 v1, s36, 36
	v_writelane_b32 v1, s37, 37
	v_writelane_b32 v1, s38, 38
	v_writelane_b32 v1, s39, 39
	v_writelane_b32 v1, s40, 40
	v_writelane_b32 v1, s41, 41
	v_writelane_b32 v1, s42, 42
	v_writelane_b32 v1, s43, 43
	v_writelane_b32 v1, s44, 44
	v_writelane_b32 v1, s45, 45
	v_writelane_b32 v1, s46, 46
	v_writelane_b32 v1, s47, 47
	v_writelane_b32 v1, s48, 48
	v_writelane_b32 v1, s49, 49
	v_writelane_b32 v1, s50, 50
	v_writelane_b32 v1, s51, 51
	v_writelane_b32 v1, s52, 52
	v_writelane_b32 v1, s53, 53
	v_writelane_b32 v1, s54, 54
	v_writelane_b32 v1, s55, 55
	v_writelane_b32 v1, s56, 56
	v_writelane_b32 v1, s57, 57
	v_writelane_b32 v1, s58, 58
	v_writelane_b32 v1, s59, 59
	v_writelane_b32 v1, s60, 60
	v_writelane_b32 v1, s61, 61
	v_writelane_b32 v1, s62, 62
	v_writelane_b32 v1, s63, 63
	v_writelane_b32 v2, s64, 0
	v_writelane_b32 v2, s65, 1
	v_writelane_b32 v2, s66, 2
	v_writelane_b32 v2, s67, 3
	v_writelane_b32 v2, s68, 4
	v_writelane_b32 v2, s69, 5
	v_writelane_b32 v2, s70, 6
	v_writelane_b32 v2, s71, 7
	v_writelane_b32 v2, s72, 8
	v_writelane_b32 v2, s73, 9
	v_writelane_b32 v2, s74, 10
	v_writelane_b32 v2, s75, 11
	v_writelane_b32 v2, s76, 12
	v_writelane_b32 v2, s77, 13
	v_writelane_b32 v2, s78, 14
	v_writelane_b32 v2, s79, 15
	v_writelane_b32 v2, s80, 16
	v_writelane_b32 v2, s81, 17
	v_writelane_b32 v2, s82, 18
	v_writelane_b32 v2, s83, 19
	v_writelane_b32 v2, s84, 20
	v_writelane_b32 v2, s85, 21
	v_writelane_b32 v2, s86, 22
	v_writelane_b32 v2, s87, 23
	v_writelane_b32 v2, s88, 24
	v_writelane_b32 v2, s89, 25
	v_writelane_b32 v2, s90, 26
	v_writelane_b32 v2, s91, 27
	v_writelane_b32 v2, s92, 28
	v_writelane_b32 v2, s93, 29
	v_writelane_b32 v2, s94, 30
	v_writelane_b32 v2, s95, 31
	v_writelane_b32 v2, s96, 32
	v_writelane_b32 v2, s97, 33
	v_writelane_b32 v2, s98, 34
	v_writelane_b32 v2, s99, 35
	s_mov_b32 vcc_lo, 0x23400
	v_lshl_add_u32 v0, v221, 2, vcc_lo
	ds_write_b32 v0, v1
	ds_write_b32 v0, v2 offset:256
	ds_write_b32 v0, v254 offset:512
	ds_write_b32 v0, v255 offset:768
	s_waitcnt lgkmcnt(0)
.Lhdr_pubdone:
	s_barrier
	s_mov_b32 s32, 0
.Lhdr_nopub:
	s_branch .LBB0_59
.LBB0_56:
	s_or_b64 exec, exec, s[8:9]
	s_waitcnt vmcnt(0)

.LBB0_540:
	s_or_b64 exec, exec, s[4:5]
	s_mov_b64 s[4:5], 0
	s_waitcnt lgkmcnt(0)
	s_mov_b32 s32, 1
